# GEMM tile headers: the generic signed division by the row-group width (always 4 for these shapes) replaced by an arithmetic shift (about 28 instructions per tile)
# baseline (speedup 1.0000x reference)
.LBB0_395:
	s_add_i32 s72, s72, 1
	s_mul_i32 s2, s72, s75
	s_mul_hi_u32 s3, s72, s64
	s_add_i32 s3, s3, s2
	s_mul_i32 s2, s72, s64
	s_add_u32 s34, s2, s33
	s_addc_u32 s35, s3, s39
	v_cmp_gt_i64_e32 vcc, s[34:35], v[144:145]
	v_cmp_lt_i64_e64 s[2:3], s[34:35], v[142:143]
	s_cbranch_vccnz .LBB0_397
	s_ashr_i32 s28, s34, 31
	s_lshr_b32 s28, s28, 29
	s_add_i32 s28, s34, s28
	s_ashr_i32 s29, s28, 3
	s_and_b32 s28, s28, -8
	s_sub_i32 s28, s34, s28
	s_cmp_lt_i32 s28, 0
	s_cselect_b32 s30, s65, 0xc0
	s_mul_i32 s28, s28, s30
	s_add_i32 s28, s28, s29
	s_mul_hi_i32 s29, s28, 0x2aaaaaab
	s_lshr_b32 s30, s29, 31
	s_ashr_i32 s29, s29, 3
	s_add_i32 s29, s29, s30
	s_lshl_b32 s30, s29, 2
	s_sub_i32 s31, 0x80, s30
	s_min_i32 s31, s31, 4
	s_mul_i32 s29, s29, 48
	s_sub_i32 s29, s28, s29
	s_ashr_i32 s28, s29, 2
	s_mul_i32 s31, s28, s31
	s_sub_i32 s29, s29, s31
	s_add_i32 s30, s30, s29

.LBB0_523:
	s_ashr_i32 s22, s24, 3
	s_add_i32 s22, s26, s22
	s_ashr_i32 s23, s22, 31
	s_lshr_b32 s23, s23, 28
	s_add_i32 s23, s22, s23
	s_ashr_i32 s24, s23, 4
	s_lshl_b32 s24, s24, 2
	s_sub_i32 s25, 0x80, s24
	s_min_i32 s25, s25, 4
	s_and_b32 s23, s23, -16
	s_sub_i32 s23, s22, s23
	s_ashr_i32 s22, s23, 2
	s_mul_i32 s25, s22, s25
	s_sub_i32 s23, s23, s25
	s_add_i32 s24, s24, s23

.LBB0_652:
	s_ashr_i32 s5, s5, 3
	s_add_i32 s5, s25, s5
	s_ashr_i32 s22, s5, 31
	s_lshr_b32 s22, s22, 26
	s_add_i32 s22, s5, s22
	s_ashr_i32 s23, s22, 6
	s_lshl_b32 s23, s23, 2
	s_sub_i32 s24, 0x80, s23
	s_min_i32 s24, s24, 4
	s_andn2_b32 s22, s22, 63
	s_sub_i32 s5, s5, s22
	s_ashr_i32 s22, s5, 2
	s_mul_i32 s24, s22, s24
	s_sub_i32 s5, s5, s24
	s_add_i32 s24, s23, s5
	s_and_b32 s26, s23, 4
	s_xor_b32 s22, s22, s26

.LBB0_865:
	s_ashr_i32 s20, s22, 3
	s_add_i32 s20, s24, s20
	s_ashr_i32 s21, s20, 31
	s_lshr_b32 s21, s21, 28
	s_add_i32 s21, s20, s21
	s_ashr_i32 s22, s21, 4
	s_lshl_b32 s22, s22, 2
	s_sub_i32 s23, 0x80, s22
	s_min_i32 s23, s23, 4
	s_and_b32 s21, s21, -16
	s_sub_i32 s21, s20, s21
	s_ashr_i32 s20, s21, 2
	s_mul_i32 s23, s20, s23
	s_sub_i32 s21, s21, s23
	s_add_i32 s22, s22, s21
